# FFN gate/up K-loop: LDS-DMA issued with SGPR base + 32-bit lane offset (no per-DMA 64-bit VALU adds)
# speedup vs baseline: 1.0197x; 1.0012x over previous
; #define PG8_STAGE(bufoff, gbase, voff) do { _Pragma("unroll") for (int _i = 0; _i < 2; ++_i) \
;         __builtin_amdgcn_global_load_lds((const unsigned*)((const char*)(gbase) + (voff)[_i]), (PG8_LAS unsigned*)(lds + (bufoff) + ldsw + _i * 8192), 16, 0, 0); } while (0)
; #define PG8_LDA(dst, b, h) do { _Pragma("unroll") for (int m = 0; m < 4; ++m) _Pragma("unroll") for (int k = 0; k < 2; ++k) dst[m][k] = *(const PG8_LAS bf16x8*)(lds + PG8_SA(b, h) + aoff + m * 2048 + k * 1024); } while (0)
; #define PG8_LDB(dst, b, h) do { _Pragma("unroll") for (int n = 0; n < 2; ++n) _Pragma("unroll") for (int k = 0; k < 2; ++k) dst[n][k] = *(const PG8_LAS bf16x8*)(lds + PG8_SB(b, h) + boff + n * 2048 + k * 1024); } while (0)
; #define PG8_MMA(ai, bj, At, Bt) do { __builtin_amdgcn_s_setprio(1); _Pragma("unroll") for (int m = 0; m < 4; ++m) _Pragma("unroll") for (int n = 0; n < 2; ++n) _Pragma("unroll") for (int k = 0; k < 2; ++k) \
;         acc[ai][bj][m][n] = __builtin_amdgcn_mfma_f32_16x16x32_bf16(Bt[n][k], At[m][k], acc[ai][bj][m][n], 0, 0, 0); __builtin_amdgcn_s_setprio(0); } while (0)
; #define PG8_WAIT_V(n) asm volatile("s_waitcnt vmcnt(" #n ")" ::: "memory")
; #define PG8_WAIT_L(n) asm volatile("s_waitcnt lgkmcnt(" #n ")" ::: "memory")
; #define PG8_BAR __builtin_amdgcn_s_barrier()
; #define PG8_SCHED __builtin_amdgcn_sched_barrier(0)
; template <class Epi, class Sched, bool ALIGN_EPI = false, bool SP2 = false>
; __device__ __forceinline__ void gemm_phase(PG8_LAS unsigned char* lds, const Gemm g, const Sched& S, const Epi& E) {
;     ...
;             PG8_LDB(B0, 0, 0); PG8_LDB(B1, 0, 1); PG8_SCHED; PG8_LDA(At, 0, 0); PG8_STAGE(PG8_SA(1, 1), a1 + hstepA, voffA);
;             PG8_WAIT_V(8); PG8_WAIT_L(0); PG8_BAR; PG8_MMA(0, 0, At, B0); PG8_MMA(0, 1, At, B1); PG8_BAR; PG8_SCHED;
;             PG8_LDA(At, 0, 1); PG8_STAGE(PG8_SB(0, 0), b2, voffB); PG8_STAGE(PG8_SB(0, 1), b2 + hstepB, voffB); PG8_STAGE(PG8_SA(0, 0), a2, voffA);
;             PG8_WAIT_V(8); PG8_WAIT_L(0); PG8_BAR; PG8_MMA(1, 0, At, B0); PG8_MMA(1, 1, At, B1); PG8_BAR; PG8_SCHED;
.LBB0_200:
	s_add_i32 s47, s24, 2
	s_add_u32 s25, s4, 0xfffc0080
	s_addc_u32 s26, s5, -1
	s_add_i32 s48, 0, 0x10000
	s_cmp_eq_u32 s39, s24
	s_cselect_b32 s27, s17, s26
	s_cselect_b32 s26, s19, s25
	s_cselect_b32 s25, s43, s46
	s_cselect_b32 s24, s44, s45
	s_add_i32 s50, 0, 0x14000
	v_add_u32_e32 v102, s48, v177
	v_add_u32_e32 v126, s50, v177
	ds_read_b128 v[86:89], v102
	ds_read_b128 v[94:97], v102 offset:1024
	ds_read_b128 v[98:101], v102 offset:2048
	ds_read_b128 v[102:105], v102 offset:3072
	ds_read_b128 v[106:109], v126
	ds_read_b128 v[110:113], v126 offset:1024
	ds_read_b128 v[118:121], v126 offset:2048
	ds_read_b128 v[126:129], v126 offset:3072
	s_add_i32 m0, s30, 0xc000
	ds_read_b128 v[202:205], v179
	ds_read_b128 v[206:209], v179 offset:1024
	ds_read_b128 v[210:213], v179 offset:2048
	ds_read_b128 v[214:217], v179 offset:3072
	ds_read_b128 v[218:221], v179 offset:4096
	ds_read_b128 v[222:225], v179 offset:5120
	ds_read_b128 v[240:243], v179 offset:6144
	ds_read_b128 v[244:247], v179 offset:7168
	global_load_lds_dwordx4 v168, s[4:5]
	s_add_i32 m0, s30, 0xe000
	s_nop 0
	global_load_lds_dwordx4 v170, s[4:5]
	s_waitcnt vmcnt(8)
	s_waitcnt lgkmcnt(0)
	s_barrier
	s_setprio 1
	s_waitcnt lgkmcnt(0)
	v_mfma_f32_16x16x32_bf16 v[158:161], v[86:89], v[202:205], v[158:161]
	v_mfma_f32_16x16x32_bf16 v[150:153], v[98:101], v[202:205], v[150:153]
	v_mfma_f32_16x16x32_bf16 v[142:145], v[86:89], v[210:213], v[142:145]
	v_mfma_f32_16x16x32_bf16 v[134:137], v[98:101], v[210:213], v[134:137]
	v_mfma_f32_16x16x32_bf16 v[122:125], v[86:89], v[218:221], v[122:125]
	v_mfma_f32_16x16x32_bf16 v[90:93], v[98:101], v[218:221], v[90:93]
	v_mfma_f32_16x16x32_bf16 v[78:81], v[86:89], v[240:243], v[78:81]
	v_mfma_f32_16x16x32_bf16 v[70:73], v[98:101], v[240:243], v[70:73]
	v_mfma_f32_16x16x32_bf16 v[158:161], v[94:97], v[206:209], v[158:161]
	v_mfma_f32_16x16x32_bf16 v[150:153], v[102:105], v[206:209], v[150:153]
	v_mfma_f32_16x16x32_bf16 v[142:145], v[94:97], v[214:217], v[142:145]
	v_mfma_f32_16x16x32_bf16 v[134:137], v[102:105], v[214:217], v[134:137]
	v_mfma_f32_16x16x32_bf16 v[122:125], v[94:97], v[222:225], v[122:125]
	v_mfma_f32_16x16x32_bf16 v[90:93], v[102:105], v[222:225], v[90:93]
	v_mfma_f32_16x16x32_bf16 v[78:81], v[94:97], v[244:247], v[78:81]
	v_mfma_f32_16x16x32_bf16 v[70:73], v[102:105], v[244:247], v[70:73]
	s_setprio 0
	s_setprio 1
	v_mfma_f32_16x16x32_bf16 v[154:157], v[106:109], v[202:205], v[154:157]
	v_mfma_f32_16x16x32_bf16 v[146:149], v[118:121], v[202:205], v[146:149]
	v_mfma_f32_16x16x32_bf16 v[138:141], v[106:109], v[210:213], v[138:141]
	v_mfma_f32_16x16x32_bf16 v[130:133], v[118:121], v[210:213], v[130:133]
	v_mfma_f32_16x16x32_bf16 v[114:117], v[106:109], v[218:221], v[114:117]
	v_mfma_f32_16x16x32_bf16 v[82:85], v[118:121], v[218:221], v[82:85]
	v_mfma_f32_16x16x32_bf16 v[74:77], v[106:109], v[240:243], v[74:77]
	v_mfma_f32_16x16x32_bf16 v[66:69], v[118:121], v[240:243], v[66:69]
	v_mfma_f32_16x16x32_bf16 v[154:157], v[110:113], v[206:209], v[154:157]
	v_mfma_f32_16x16x32_bf16 v[146:149], v[126:129], v[206:209], v[146:149]
	v_mfma_f32_16x16x32_bf16 v[138:141], v[110:113], v[214:217], v[138:141]
	v_mfma_f32_16x16x32_bf16 v[130:133], v[126:129], v[214:217], v[130:133]
	v_mfma_f32_16x16x32_bf16 v[114:117], v[110:113], v[222:225], v[114:117]
	v_mfma_f32_16x16x32_bf16 v[82:85], v[126:129], v[222:225], v[82:85]
	v_mfma_f32_16x16x32_bf16 v[74:77], v[110:113], v[244:247], v[74:77]
	v_mfma_f32_16x16x32_bf16 v[66:69], v[126:129], v[244:247], v[66:69]
	s_setprio 0
	s_barrier
	s_add_i32 s48, s48, s28
	s_mov_b32 m0, s48
	ds_read_b128 v[202:205], v179 offset:16384
	ds_read_b128 v[206:209], v179 offset:17408
	ds_read_b128 v[210:213], v179 offset:18432
	ds_read_b128 v[214:217], v179 offset:19456
	ds_read_b128 v[218:221], v179 offset:20480
	ds_read_b128 v[222:225], v179 offset:21504
	ds_read_b128 v[240:243], v179 offset:22528
	ds_read_b128 v[244:247], v179 offset:23552
	global_load_lds_dwordx4 v64, s[24:25]
	s_add_i32 m0, s48, 0x2000
	s_add_u32 s48, s24, 0x40000
	s_addc_u32 s49, s25, 0
	s_add_i32 s50, s50, s28
	global_load_lds_dwordx4 v162, s[24:25]
	s_mov_b32 m0, s50
	s_nop 0
	global_load_lds_dwordx4 v64, s[48:49]
	s_add_i32 m0, s50, 0x2000
	s_nop 0
	global_load_lds_dwordx4 v162, s[48:49]
	s_mov_b32 m0, s30
	s_nop 0
	global_load_lds_dwordx4 v166, s[26:27]
	s_mov_b32 m0, s31
	s_nop 0
	global_load_lds_dwordx4 v164, s[26:27]
	s_waitcnt vmcnt(8)
	s_waitcnt lgkmcnt(0)
	s_barrier
	s_setprio 1
	s_waitcnt lgkmcnt(0)
	v_mfma_f32_16x16x32_bf16 v[60:63], v[86:89], v[202:205], v[60:63]
	v_mfma_f32_16x16x32_bf16 v[52:55], v[98:101], v[202:205], v[52:55]
	v_mfma_f32_16x16x32_bf16 v[44:47], v[86:89], v[210:213], v[44:47]
	v_mfma_f32_16x16x32_bf16 v[36:39], v[98:101], v[210:213], v[36:39]
	v_mfma_f32_16x16x32_bf16 v[28:31], v[86:89], v[218:221], v[28:31]
	v_mfma_f32_16x16x32_bf16 v[20:23], v[98:101], v[218:221], v[20:23]
	v_mfma_f32_16x16x32_bf16 v[12:15], v[86:89], v[240:243], v[12:15]
	v_mfma_f32_16x16x32_bf16 v[4:7], v[98:101], v[240:243], v[4:7]
	v_mfma_f32_16x16x32_bf16 v[60:63], v[94:97], v[206:209], v[60:63]
	v_mfma_f32_16x16x32_bf16 v[52:55], v[102:105], v[206:209], v[52:55]
	v_mfma_f32_16x16x32_bf16 v[44:47], v[94:97], v[214:217], v[44:47]
	v_mfma_f32_16x16x32_bf16 v[36:39], v[102:105], v[214:217], v[36:39]
	v_mfma_f32_16x16x32_bf16 v[28:31], v[94:97], v[222:225], v[28:31]
	v_mfma_f32_16x16x32_bf16 v[20:23], v[102:105], v[222:225], v[20:23]
	v_mfma_f32_16x16x32_bf16 v[12:15], v[94:97], v[244:247], v[12:15]
	v_mfma_f32_16x16x32_bf16 v[4:7], v[102:105], v[244:247], v[4:7]
	s_setprio 0
	s_setprio 1
	v_mfma_f32_16x16x32_bf16 v[56:59], v[106:109], v[202:205], v[56:59]
	v_mfma_f32_16x16x32_bf16 v[48:51], v[118:121], v[202:205], v[48:51]
	v_mfma_f32_16x16x32_bf16 v[40:43], v[106:109], v[210:213], v[40:43]
	v_mfma_f32_16x16x32_bf16 v[32:35], v[118:121], v[210:213], v[32:35]
	v_mfma_f32_16x16x32_bf16 v[24:27], v[106:109], v[218:221], v[24:27]
	v_mfma_f32_16x16x32_bf16 v[16:19], v[118:121], v[218:221], v[16:19]
	v_mfma_f32_16x16x32_bf16 v[8:11], v[106:109], v[240:243], v[8:11]
	v_mfma_f32_16x16x32_bf16 v[0:3], v[118:121], v[240:243], v[0:3]
	v_mfma_f32_16x16x32_bf16 v[56:59], v[110:113], v[206:209], v[56:59]
	v_mfma_f32_16x16x32_bf16 v[48:51], v[126:129], v[206:209], v[48:51]
	v_mfma_f32_16x16x32_bf16 v[40:43], v[110:113], v[214:217], v[40:43]
	v_mfma_f32_16x16x32_bf16 v[32:35], v[126:129], v[214:217], v[32:35]
	v_mfma_f32_16x16x32_bf16 v[24:27], v[110:113], v[222:225], v[24:27]
	v_mfma_f32_16x16x32_bf16 v[16:19], v[126:129], v[222:225], v[16:19]
	v_mfma_f32_16x16x32_bf16 v[8:11], v[110:113], v[244:247], v[8:11]
	v_mfma_f32_16x16x32_bf16 v[0:3], v[126:129], v[244:247], v[0:3]
	s_setprio 0
	s_barrier
; #define PG8_STAGE(bufoff, gbase, voff) do { _Pragma("unroll") for (int _i = 0; _i < 2; ++_i) \
;         __builtin_amdgcn_global_load_lds((const unsigned*)((const char*)(gbase) + (voff)[_i]), (PG8_LAS unsigned*)(lds + (bufoff) + ldsw + _i * 8192), 16, 0, 0); } while (0)
; #define PG8_LDA(dst, b, h) do { _Pragma("unroll") for (int m = 0; m < 4; ++m) _Pragma("unroll") for (int k = 0; k < 2; ++k) dst[m][k] = *(const PG8_LAS bf16x8*)(lds + PG8_SA(b, h) + aoff + m * 2048 + k * 1024); } while (0)
; #define PG8_LDB(dst, b, h) do { _Pragma("unroll") for (int n = 0; n < 2; ++n) _Pragma("unroll") for (int k = 0; k < 2; ++k) dst[n][k] = *(const PG8_LAS bf16x8*)(lds + PG8_SB(b, h) + boff + n * 2048 + k * 1024); } while (0)
; #define PG8_MMA(ai, bj, At, Bt) do { __builtin_amdgcn_s_setprio(1); _Pragma("unroll") for (int m = 0; m < 4; ++m) _Pragma("unroll") for (int n = 0; n < 2; ++n) _Pragma("unroll") for (int k = 0; k < 2; ++k) \
;         acc[ai][bj][m][n] = __builtin_amdgcn_mfma_f32_16x16x32_bf16(Bt[n][k], At[m][k], acc[ai][bj][m][n], 0, 0, 0); __builtin_amdgcn_s_setprio(0); } while (0)
; #define PG8_WAIT_V(n) asm volatile("s_waitcnt vmcnt(" #n ")" ::: "memory")
; #define PG8_WAIT_L(n) asm volatile("s_waitcnt lgkmcnt(" #n ")" ::: "memory")
; #define PG8_BAR __builtin_amdgcn_s_barrier()
; #define PG8_SCHED __builtin_amdgcn_sched_barrier(0)
; template <class Epi, class Sched, bool ALIGN_EPI = false, bool SP2 = false>
; __device__ __forceinline__ void gemm_phase(PG8_LAS unsigned char* lds, const Gemm g, const Sched& S, const Epi& E) {
;     ...
;             PG8_LDB(B0, 1, 0); PG8_LDB(B1, 1, 1); PG8_SCHED; PG8_LDA(At, 1, 0); PG8_STAGE(PG8_SA(0, 1), a2 + hstepA, voffA);
;             PG8_WAIT_V(8); PG8_WAIT_L(0); PG8_BAR; PG8_MMA(0, 0, At, B0); PG8_MMA(0, 1, At, B1); PG8_BAR; PG8_SCHED;
;             PG8_LDA(At, 1, 1); PG8_STAGE(PG8_SB(1, 0), b3, voffB); PG8_STAGE(PG8_SB(1, 1), b3 + hstepB, voffB); PG8_STAGE(PG8_SA(1, 0), a3, voffA);
;             PG8_WAIT_V(8); PG8_WAIT_L(0); PG8_BAR; PG8_MMA(1, 0, At, B0); PG8_MMA(1, 1, At, B1); PG8_BAR; PG8_SCHED;
	s_add_i32 s48, 0, 0x18000
	s_add_i32 s49, 0, 0x1c000
	v_add_u32_e32 v102, s48, v177
	v_add_u32_e32 v126, s49, v177
	ds_read_b128 v[86:89], v102
	ds_read_b128 v[94:97], v102 offset:1024
	ds_read_b128 v[98:101], v102 offset:2048
	ds_read_b128 v[102:105], v102 offset:3072
	ds_read_b128 v[106:109], v126
	ds_read_b128 v[110:113], v126 offset:1024
	ds_read_b128 v[118:121], v126 offset:2048
	ds_read_b128 v[126:129], v126 offset:3072
	s_add_u32 s26, s26, 0x40000
	s_addc_u32 s27, s27, 0
	s_add_u32 s100, s26, 0xfffc0080
	s_addc_u32 s101, s27, -1
	s_mov_b32 m0, s34
	ds_read_b128 v[202:205], v179 offset:32768
	ds_read_b128 v[206:209], v179 offset:33792
	ds_read_b128 v[210:213], v179 offset:34816
	ds_read_b128 v[214:217], v179 offset:35840
	ds_read_b128 v[218:221], v179 offset:36864
	ds_read_b128 v[222:225], v179 offset:37888
	ds_read_b128 v[240:243], v179 offset:38912
	ds_read_b128 v[244:247], v179 offset:39936
	global_load_lds_dwordx4 v166, s[26:27]
	s_mov_b32 m0, s35
	s_nop 0
	global_load_lds_dwordx4 v164, s[26:27]
	s_waitcnt vmcnt(8)
	s_waitcnt lgkmcnt(0)
	s_barrier
	s_setprio 1
	s_waitcnt lgkmcnt(0)
	v_mfma_f32_16x16x32_bf16 v[158:161], v[86:89], v[202:205], v[158:161]
	v_mfma_f32_16x16x32_bf16 v[150:153], v[98:101], v[202:205], v[150:153]
	v_mfma_f32_16x16x32_bf16 v[142:145], v[86:89], v[210:213], v[142:145]
	v_mfma_f32_16x16x32_bf16 v[134:137], v[98:101], v[210:213], v[134:137]
	v_mfma_f32_16x16x32_bf16 v[122:125], v[86:89], v[218:221], v[122:125]
	v_mfma_f32_16x16x32_bf16 v[90:93], v[98:101], v[218:221], v[90:93]
	v_mfma_f32_16x16x32_bf16 v[78:81], v[86:89], v[240:243], v[78:81]
	v_mfma_f32_16x16x32_bf16 v[70:73], v[98:101], v[240:243], v[70:73]
	v_mfma_f32_16x16x32_bf16 v[158:161], v[94:97], v[206:209], v[158:161]
	v_mfma_f32_16x16x32_bf16 v[150:153], v[102:105], v[206:209], v[150:153]
	v_mfma_f32_16x16x32_bf16 v[142:145], v[94:97], v[214:217], v[142:145]
	v_mfma_f32_16x16x32_bf16 v[134:137], v[102:105], v[214:217], v[134:137]
	v_mfma_f32_16x16x32_bf16 v[122:125], v[94:97], v[222:225], v[122:125]
	v_mfma_f32_16x16x32_bf16 v[90:93], v[102:105], v[222:225], v[90:93]
	v_mfma_f32_16x16x32_bf16 v[78:81], v[94:97], v[244:247], v[78:81]
	v_mfma_f32_16x16x32_bf16 v[70:73], v[102:105], v[244:247], v[70:73]
	s_setprio 0
	s_setprio 1
	v_mfma_f32_16x16x32_bf16 v[154:157], v[106:109], v[202:205], v[154:157]
	v_mfma_f32_16x16x32_bf16 v[146:149], v[118:121], v[202:205], v[146:149]
	v_mfma_f32_16x16x32_bf16 v[138:141], v[106:109], v[210:213], v[138:141]
	v_mfma_f32_16x16x32_bf16 v[130:133], v[118:121], v[210:213], v[130:133]
	v_mfma_f32_16x16x32_bf16 v[114:117], v[106:109], v[218:221], v[114:117]
	v_mfma_f32_16x16x32_bf16 v[82:85], v[118:121], v[218:221], v[82:85]
	v_mfma_f32_16x16x32_bf16 v[74:77], v[106:109], v[240:243], v[74:77]
	v_mfma_f32_16x16x32_bf16 v[66:69], v[118:121], v[240:243], v[66:69]
	v_mfma_f32_16x16x32_bf16 v[154:157], v[110:113], v[206:209], v[154:157]
	v_mfma_f32_16x16x32_bf16 v[146:149], v[126:129], v[206:209], v[146:149]
	v_mfma_f32_16x16x32_bf16 v[138:141], v[110:113], v[214:217], v[138:141]
	v_mfma_f32_16x16x32_bf16 v[130:133], v[126:129], v[214:217], v[130:133]
	v_mfma_f32_16x16x32_bf16 v[114:117], v[110:113], v[222:225], v[114:117]
	v_mfma_f32_16x16x32_bf16 v[82:85], v[126:129], v[222:225], v[82:85]
	v_mfma_f32_16x16x32_bf16 v[74:77], v[110:113], v[244:247], v[74:77]
	v_mfma_f32_16x16x32_bf16 v[66:69], v[126:129], v[244:247], v[66:69]
	s_setprio 0
	s_barrier
	s_add_i32 s26, s48, s28
	s_add_u32 s24, s24, 0x80
	s_addc_u32 s25, s25, 0
	s_mov_b32 m0, s26
	ds_read_b128 v[202:205], v179 offset:49152
	ds_read_b128 v[206:209], v179 offset:50176
	ds_read_b128 v[210:213], v179 offset:51200
	ds_read_b128 v[214:217], v179 offset:52224
	ds_read_b128 v[218:221], v179 offset:53248
	ds_read_b128 v[222:225], v179 offset:54272
	ds_read_b128 v[240:243], v179 offset:55296
	ds_read_b128 v[244:247], v179 offset:56320
	global_load_lds_dwordx4 v64, s[24:25]
	s_add_i32 m0, s26, 0x2000
	s_add_i32 s26, s49, s28
	global_load_lds_dwordx4 v162, s[24:25]
	s_add_u32 s24, s24, 0x40000
	s_addc_u32 s25, s25, 0
	s_mov_b32 m0, s26
	s_nop 0
	global_load_lds_dwordx4 v64, s[24:25]
	s_add_i32 m0, s26, 0x2000
	s_nop 0
	global_load_lds_dwordx4 v162, s[24:25]
	s_mov_b32 m0, s37
	s_nop 0
	global_load_lds_dwordx4 v166, s[100:101]
	s_mov_b32 m0, s38
	s_nop 0
	global_load_lds_dwordx4 v164, s[100:101]
	s_waitcnt vmcnt(8)
	s_waitcnt lgkmcnt(0)
	s_barrier
	s_setprio 1
	s_waitcnt lgkmcnt(0)
	v_mfma_f32_16x16x32_bf16 v[60:63], v[86:89], v[202:205], v[60:63]
	v_mfma_f32_16x16x32_bf16 v[52:55], v[98:101], v[202:205], v[52:55]
	v_mfma_f32_16x16x32_bf16 v[44:47], v[86:89], v[210:213], v[44:47]
	v_mfma_f32_16x16x32_bf16 v[36:39], v[98:101], v[210:213], v[36:39]
	v_mfma_f32_16x16x32_bf16 v[28:31], v[86:89], v[218:221], v[28:31]
	v_mfma_f32_16x16x32_bf16 v[20:23], v[98:101], v[218:221], v[20:23]
	v_mfma_f32_16x16x32_bf16 v[12:15], v[86:89], v[240:243], v[12:15]
	v_mfma_f32_16x16x32_bf16 v[4:7], v[98:101], v[240:243], v[4:7]
	v_mfma_f32_16x16x32_bf16 v[60:63], v[94:97], v[206:209], v[60:63]
	v_mfma_f32_16x16x32_bf16 v[52:55], v[102:105], v[206:209], v[52:55]
	v_mfma_f32_16x16x32_bf16 v[44:47], v[94:97], v[214:217], v[44:47]
	v_mfma_f32_16x16x32_bf16 v[36:39], v[102:105], v[214:217], v[36:39]
	v_mfma_f32_16x16x32_bf16 v[28:31], v[94:97], v[222:225], v[28:31]
	v_mfma_f32_16x16x32_bf16 v[20:23], v[102:105], v[222:225], v[20:23]
	v_mfma_f32_16x16x32_bf16 v[12:15], v[94:97], v[244:247], v[12:15]
	v_mfma_f32_16x16x32_bf16 v[4:7], v[102:105], v[244:247], v[4:7]
	s_setprio 0
	s_setprio 1
	v_mfma_f32_16x16x32_bf16 v[56:59], v[106:109], v[202:205], v[56:59]
	v_mfma_f32_16x16x32_bf16 v[48:51], v[118:121], v[202:205], v[48:51]
	v_mfma_f32_16x16x32_bf16 v[40:43], v[106:109], v[210:213], v[40:43]
	v_mfma_f32_16x16x32_bf16 v[32:35], v[118:121], v[210:213], v[32:35]
	v_mfma_f32_16x16x32_bf16 v[24:27], v[106:109], v[218:221], v[24:27]
	v_mfma_f32_16x16x32_bf16 v[16:19], v[118:121], v[218:221], v[16:19]
	v_mfma_f32_16x16x32_bf16 v[8:11], v[106:109], v[240:243], v[8:11]
	v_mfma_f32_16x16x32_bf16 v[0:3], v[118:121], v[240:243], v[0:3]
	v_mfma_f32_16x16x32_bf16 v[56:59], v[110:113], v[206:209], v[56:59]
	v_mfma_f32_16x16x32_bf16 v[48:51], v[126:129], v[206:209], v[48:51]
	v_mfma_f32_16x16x32_bf16 v[40:43], v[110:113], v[214:217], v[40:43]
	v_mfma_f32_16x16x32_bf16 v[32:35], v[126:129], v[214:217], v[32:35]
	v_mfma_f32_16x16x32_bf16 v[24:27], v[110:113], v[222:225], v[24:27]
	v_mfma_f32_16x16x32_bf16 v[16:19], v[126:129], v[222:225], v[16:19]
	v_mfma_f32_16x16x32_bf16 v[8:11], v[110:113], v[244:247], v[8:11]
	v_mfma_f32_16x16x32_bf16 v[0:3], v[126:129], v[244:247], v[0:3]
	s_setprio 0
	s_barrier
	s_add_u32 s4, s4, 0x100
	s_addc_u32 s5, s5, 0
	s_add_u32 s45, s45, 0x100
	s_addc_u32 s46, s46, 0
	s_cmp_ge_i32 s47, s36
	s_mov_b32 s24, s47
	s_cbranch_scc0 .LBB0_200

; __global__ void __launch_bounds__(NTHR, 2) fwd_kernel(Args a) {
	.amdhsa_kernel _Z10fwd_kernel4Args
		.amdhsa_group_segment_fixed_size 0
		.amdhsa_private_segment_fixed_size 0
		.amdhsa_kernarg_size 448
		.amdhsa_user_sgpr_count 2
		.amdhsa_user_sgpr_dispatch_ptr 0
		.amdhsa_user_sgpr_queue_ptr 0
		.amdhsa_user_sgpr_kernarg_segment_ptr 1
		.amdhsa_user_sgpr_dispatch_id 0
		.amdhsa_user_sgpr_kernarg_preload_length 0
		.amdhsa_user_sgpr_kernarg_preload_offset 0
		.amdhsa_user_sgpr_private_segment_size 0
		.amdhsa_uses_dynamic_stack 0
		.amdhsa_enable_private_segment 0
		.amdhsa_system_sgpr_workgroup_id_x 1
		.amdhsa_system_sgpr_workgroup_id_y 0
		.amdhsa_system_sgpr_workgroup_id_z 0
		.amdhsa_system_sgpr_workgroup_info 0
		.amdhsa_system_vgpr_workitem_id 2
		.amdhsa_next_free_vgpr 256
		.amdhsa_next_free_sgpr 102
		.amdhsa_accum_offset 256
		.amdhsa_reserve_vcc 1
		.amdhsa_float_round_mode_32 0
		.amdhsa_float_round_mode_16_64 0
		.amdhsa_float_denorm_mode_32 3
		.amdhsa_float_denorm_mode_16_64 3
		.amdhsa_dx10_clamp 1
		.amdhsa_ieee_mode 1
		.amdhsa_fp16_overflow 0
		.amdhsa_tg_split 0
		.amdhsa_exception_fp_ieee_invalid_op 0
		.amdhsa_exception_fp_denorm_src 0
		.amdhsa_exception_fp_ieee_div_zero 0
		.amdhsa_exception_fp_ieee_overflow 0
		.amdhsa_exception_fp_ieee_underflow 0
		.amdhsa_exception_fp_ieee_inexact 0
		.amdhsa_exception_int_div_zero 0
	.end_amdhsa_kernel

; __global__ void __launch_bounds__(NTHR, 2) fwd_kernel(Args a) {
amdhsa.kernels:
  - .agpr_count:     0
    .args:
      - .offset:         0
        .size:           192
        .value_kind:     by_value
      - .offset:         192
        .size:           4
        .value_kind:     hidden_block_count_x
      - .offset:         196
        .size:           4
        .value_kind:     hidden_block_count_y
      - .offset:         200
        .size:           4
        .value_kind:     hidden_block_count_z
      - .offset:         204
        .size:           2
        .value_kind:     hidden_group_size_x
      - .offset:         206
        .size:           2
        .value_kind:     hidden_group_size_y
      - .offset:         208
        .size:           2
        .value_kind:     hidden_group_size_z
      - .offset:         210
        .size:           2
        .value_kind:     hidden_remainder_x
      - .offset:         212
        .size:           2
        .value_kind:     hidden_remainder_y
      - .offset:         214
        .size:           2
        .value_kind:     hidden_remainder_z
      - .offset:         232
        .size:           8
        .value_kind:     hidden_global_offset_x
      - .offset:         240
        .size:           8
        .value_kind:     hidden_global_offset_y
      - .offset:         248
        .size:           8
        .value_kind:     hidden_global_offset_z
      - .offset:         256
        .size:           2
        .value_kind:     hidden_grid_dims
      - .offset:         280
        .size:           8
        .value_kind:     hidden_multigrid_sync_arg
      - .offset:         312
        .size:           4
        .value_kind:     hidden_dynamic_lds_size
    .group_segment_fixed_size: 0
    .kernarg_segment_align: 8
    .kernarg_segment_size: 448
    .language:       OpenCL C
    .language_version:
      - 2
      - 0
    .max_flat_workgroup_size: 512
    .name:           _Z10fwd_kernel4Args
    .private_segment_fixed_size: 0
    .sgpr_count:     108
    .sgpr_spill_count: 75
    .symbol:         _Z10fwd_kernel4Args.kd
    .uniform_work_group_size: 1
    .uses_dynamic_stack: false
    .vgpr_count:     256
    .vgpr_spill_count: 0
    .wavefront_size: 64
